# P1 q/k epilogue: the 16 cross-row ds_bpermute reductions (xor 16, xor 32) replaced by v_permlane16_swap / v_permlane32_swap
# baseline (speedup 1.0000x reference)
.LBB0_326:
	s_and_b64 vcc, exec, s[68:69]
	s_cbranch_vccz .LBB0_335
	s_and_b64 s[54:55], s[4:5], exec
	s_cselect_b32 s54, 0, 0x1000000
	s_add_u32 s68, s10, s54
	s_addc_u32 s69, s11, 0
	s_and_b64 s[54:55], s[4:5], exec
	s_cselect_b32 s55, s43, s45
	s_cselect_b32 s54, s42, s44
	v_lshlrev_b32_e32 v150, 2, v140
	global_load_dwordx4 v[128:131], v150, s[54:55]
	global_load_dwordx4 v[132:135], v150, s[54:55] offset:128
	global_load_dwordx4 v[136:139], v150, s[54:55] offset:16
	global_load_dwordx4 v[192:195], v150, s[54:55] offset:144
	v_cndmask_b32_e64 v174, 1.0, v186, s[4:5]
	s_lshl_b32 s4, s63, 9
	s_add_u32 s4, s68, s4
	s_addc_u32 s5, s69, 0
	s_add_u32 s4, s4, s91
	v_lshlrev_b32_e32 v150, 1, v140
	v_lshlrev_b32_e32 v196, 8, v162
	v_mov_b32_e32 v164, v125
	v_mov_b32_e32 v165, v117
	s_addc_u32 s5, s5, 0
	v_pk_mul_f32 v[204:205], v[164:165], v[164:165]
	v_lshl_add_u64 v[164:165], s[4:5], 0, v[150:151]
	v_and_b32_e32 v150, 0xfcf00, v196
	v_lshl_add_u64 v[210:211], v[152:153], 0, v[150:151]
	global_load_dwordx4 v[196:199], v[210:211], off offset:16
	global_load_dwordx4 v[200:203], v[210:211], off
	v_mov_b32_e32 v170, v127
	v_mov_b32_e32 v171, v119
	v_mov_b32_e32 v166, v124
	v_mov_b32_e32 v167, v116
	v_mov_b32_e32 v168, v126
	v_mov_b32_e32 v169, v118
	v_mov_b32_e32 v176, v121
	v_mov_b32_e32 v177, v113
	v_pk_mul_f32 v[170:171], v[170:171], v[170:171]
	v_and_b32_e32 v175, 64, v187
	v_mov_b32_e32 v172, v120
	v_mov_b32_e32 v173, v112
	v_mov_b32_e32 v190, v123
	v_mov_b32_e32 v191, v115
	v_pk_mul_f32 v[176:177], v[176:177], v[176:177]
	v_pk_fma_f32 v[166:167], v[166:167], v[166:167], v[204:205]
	v_pk_fma_f32 v[168:169], v[168:169], v[168:169], v[170:171]
	v_xor_b32_e32 v163, 16, v187
	v_mov_b32_e32 v188, v122
	v_mov_b32_e32 v189, v114
	v_add_u32_e32 v175, 64, v175
	v_pk_mul_f32 v[190:191], v[190:191], v[190:191]
	v_pk_fma_f32 v[170:171], v[172:173], v[172:173], v[176:177]
	v_pk_add_f32 v[166:167], v[166:167], v[168:169]
	v_xor_b32_e32 v206, 32, v187
	v_cmp_lt_i32_e32 vcc, v163, v175
	v_pk_fma_f32 v[172:173], v[188:189], v[188:189], v[190:191]
	v_pk_add_f32 v[166:167], v[166:167], v[170:171]
	v_cndmask_b32_e32 v150, v187, v163, vcc
	v_pk_add_f32 v[166:167], v[172:173], v[166:167]
	v_add_u32_e32 v189, s59, v179
	v_cmp_lt_i32_e32 vcc, v206, v175
	v_lshlrev_b32_e32 v188, 2, v150
	v_add_f32_e32 v150, v166, v167
	v_cndmask_b32_e32 v166, v187, v206, vcc
	ds_read_b32 v177, v189
	global_load_dwordx4 v[204:207], v[210:211], off offset:48
	s_nop 0
	global_load_dwordx4 v[210:213], v[210:211], off offset:32
	v_mov_b32_e32 v163, v150
	s_nop 1
	v_permlane16_swap_b32_e32 v150, v163
	v_lshlrev_b32_e32 v190, 2, v166
	v_or_b32_e32 v176, 16, v162
	s_waitcnt lgkmcnt(0)
	v_add_f32_e32 v150, v150, v163
	v_mov_b32_e32 v163, v150
	s_nop 1
	v_permlane32_swap_b32_e32 v150, v163
	s_waitcnt lgkmcnt(0)
	v_add_f32_e32 v150, v150, v163
	v_mul_f32_e32 v150, v177, v150
	v_mul_f32_e32 v150, v177, v150
	v_fmamk_f32 v150, v150, 0x3c800000, v183
	v_mul_f32_e32 v163, 0x4f800000, v150
	v_cmp_gt_f32_e32 vcc, s92, v150
	s_waitcnt vmcnt(0)
	v_pk_mul_f32 v[172:173], v[174:175], v[128:129] op_sel_hi:[0,1]
	v_cndmask_b32_e32 v163, v150, v163, vcc
	v_sqrt_f32_e32 v191, v163
	v_lshlrev_b32_e32 v128, 8, v176
	v_and_b32_e32 v150, 0xfdf00, v128
	v_pk_mul_f32 v[170:171], v[174:175], v[130:131] op_sel_hi:[0,1]
	v_add_u32_e32 v128, -1, v191
	v_fma_f32 v129, -v128, v191, v163
	v_cmp_ge_f32_e64 s[4:5], 0, v129
	v_add_u32_e32 v129, 1, v191
	v_fma_f32 v130, -v129, v191, v163
	v_cndmask_b32_e64 v128, v191, v128, s[4:5]
	v_cmp_lt_f32_e64 s[4:5], 0, v130
	v_pk_mul_f32 v[214:215], v[174:175], v[134:135] op_sel_hi:[0,1]
	v_pk_mul_f32 v[216:217], v[174:175], v[132:133] op_sel_hi:[0,1]
	v_cndmask_b32_e64 v128, v128, v129, s[4:5]
	v_mul_f32_e32 v129, 0x37800000, v128
	v_cndmask_b32_e32 v128, v128, v129, vcc
	v_cmp_class_f32_e32 vcc, v163, v184
	v_pk_mul_f32 v[166:167], v[174:175], v[138:139] op_sel_hi:[0,1]
	v_pk_mul_f32 v[168:169], v[174:175], v[136:137] op_sel_hi:[0,1]
	v_pk_mul_f32 v[218:219], v[174:175], v[194:195] op_sel_hi:[0,1]
	v_pk_mul_f32 v[220:221], v[174:175], v[192:193] op_sel_hi:[0,1]
	v_lshl_add_u64 v[174:175], v[152:153], 0, v[150:151]
	v_cndmask_b32_e32 v150, v128, v163, vcc
	v_div_scale_f32 v163, s[4:5], v150, v150, v177
	v_rcp_f32_e32 v191, v163
	global_load_dwordx4 v[128:131], v[174:175], off offset:48
	global_load_dwordx4 v[132:135], v[174:175], off offset:32
	global_load_dwordx4 v[136:139], v[174:175], off offset:16
	global_load_dwordx4 v[192:195], v[174:175], off
	v_fma_f32 v174, -v163, v191, 1.0
	v_fmac_f32_e32 v191, v174, v191
	v_div_scale_f32 v174, vcc, v177, v150, v177
	v_mul_f32_e32 v175, v174, v191
	v_fma_f32 v222, -v163, v175, v174
	v_fmac_f32_e32 v175, v222, v191
	v_fma_f32 v163, -v163, v175, v174
	v_div_fmas_f32 v163, v163, v191, v175
	v_div_fixup_f32 v150, v163, v150, v177
	v_mov_b32_e32 v174, v120
	v_mov_b32_e32 v175, v124
	v_mov_b32_e32 v124, v121
	v_pk_mul_f32 v[222:223], v[174:175], v[150:151] op_sel_hi:[1,0]
	v_mov_b32_e32 v175, v172
	v_pk_mul_f32 v[120:121], v[124:125], v[150:151] op_sel_hi:[1,0]
	v_mov_b32_e32 v172, v217
	v_pk_mul_f32 v[120:121], v[172:173], v[120:121]
	v_mov_b32_e32 v174, v216
	v_pk_mul_f32 v[124:125], v[202:203], v[120:121] op_sel:[0,1] op_sel_hi:[1,0]
	v_pk_mul_f32 v[120:121], v[202:203], v[120:121]
	v_pk_mul_f32 v[222:223], v[174:175], v[222:223]
	v_add_f32_e32 v202, v120, v121
	v_mov_b32_e32 v120, v122
	v_mov_b32_e32 v121, v126
	v_sub_f32_e32 v191, v124, v125
	v_pk_mul_f32 v[124:125], v[120:121], v[150:151] op_sel_hi:[1,0]
	v_mov_b32_e32 v120, v214
	v_mov_b32_e32 v121, v170
	v_mov_b32_e32 v126, v123
	v_pk_mul_f32 v[224:225], v[200:201], v[222:223] op_sel:[0,1] op_sel_hi:[1,0]
	v_pk_mul_f32 v[200:201], v[200:201], v[222:223]
	v_pk_mul_f32 v[124:125], v[120:121], v[124:125]
	v_pk_mul_f32 v[122:123], v[126:127], v[150:151] op_sel_hi:[1,0]
	v_mov_b32_e32 v170, v215
	v_add_f32_e32 v177, v200, v201
	v_pk_mul_f32 v[200:201], v[196:197], v[124:125] op_sel:[0,1] op_sel_hi:[1,0]
	v_pk_mul_f32 v[124:125], v[196:197], v[124:125]
	v_pk_mul_f32 v[122:123], v[170:171], v[122:123]
	v_add_f32_e32 v196, v124, v125
	v_pk_mul_f32 v[124:125], v[198:199], v[122:123] op_sel:[0,1] op_sel_hi:[1,0]
	v_pk_mul_f32 v[122:123], v[198:199], v[122:123]
	v_sub_f32_e32 v197, v124, v125
	v_add_f32_e32 v198, v122, v123
	v_mov_b32_e32 v122, v112
	v_mov_b32_e32 v123, v116
	v_mov_b32_e32 v116, v113
	v_pk_mul_f32 v[124:125], v[122:123], v[150:151] op_sel_hi:[1,0]
	v_mov_b32_e32 v123, v168
	v_pk_mul_f32 v[112:113], v[116:117], v[150:151] op_sel_hi:[1,0]
	v_mov_b32_e32 v168, v221
	v_mov_b32_e32 v122, v220
	v_pk_mul_f32 v[112:113], v[168:169], v[112:113]
	v_pk_mul_f32 v[124:125], v[122:123], v[124:125]
	v_pk_mul_f32 v[116:117], v[212:213], v[112:113] op_sel:[0,1] op_sel_hi:[1,0]
	v_pk_mul_f32 v[112:113], v[212:213], v[112:113]
	v_sub_f32_e32 v200, v200, v201
	v_pk_mul_f32 v[126:127], v[210:211], v[124:125] op_sel:[0,1] op_sel_hi:[1,0]
	v_add_f32_e32 v201, v112, v113
	v_mov_b32_e32 v112, v114
	v_mov_b32_e32 v113, v118
	v_sub_f32_e32 v126, v126, v127
	v_sub_f32_e32 v127, v116, v117
	v_pk_mul_f32 v[116:117], v[112:113], v[150:151] op_sel_hi:[1,0]
	v_mov_b32_e32 v112, v218
	v_mov_b32_e32 v113, v166
	v_mov_b32_e32 v118, v115
	v_pk_mul_f32 v[124:125], v[210:211], v[124:125]
	v_pk_mul_f32 v[116:117], v[112:113], v[116:117]
	v_pk_mul_f32 v[114:115], v[118:119], v[150:151] op_sel_hi:[1,0]
	v_mov_b32_e32 v166, v219
	v_add_f32_e32 v199, v124, v125
	v_pk_mul_f32 v[124:125], v[204:205], v[116:117] op_sel:[0,1] op_sel_hi:[1,0]
	v_pk_mul_f32 v[116:117], v[204:205], v[116:117]
	v_pk_mul_f32 v[114:115], v[166:167], v[114:115]
	v_add_f32_e32 v203, v116, v117
	v_pk_mul_f32 v[116:117], v[206:207], v[114:115] op_sel:[0,1] op_sel_hi:[1,0]
	v_sub_f32_e32 v124, v124, v125
	v_sub_f32_e32 v117, v116, v117
	v_pk_mul_f32 v[114:115], v[206:207], v[114:115]
	v_sub_f32_e32 v163, v224, v225
	v_add_f32_e32 v150, v114, v115
	v_cvt_pk_bf16_f32 v114, v163, v191
	v_cvt_pk_bf16_f32 v115, v200, v197
	v_cvt_pk_bf16_f32 v116, v126, v127
	v_cvt_pk_bf16_f32 v117, v124, v117
	v_mov_b32_e32 v124, v109
	v_mov_b32_e32 v125, v101
	v_mov_b32_e32 v118, v108
	v_mov_b32_e32 v119, v100
	v_pk_mul_f32 v[124:125], v[124:125], v[124:125]
	v_mov_b32_e32 v126, v111
	v_mov_b32_e32 v127, v103
	v_pk_fma_f32 v[118:119], v[118:119], v[118:119], v[124:125]
	v_mov_b32_e32 v124, v110
	v_mov_b32_e32 v125, v102
	v_pk_mul_f32 v[126:127], v[126:127], v[126:127]
	v_ashrrev_i32_e32 v163, 31, v162
	v_pk_fma_f32 v[124:125], v[124:125], v[124:125], v[126:127]
	v_mov_b32_e32 v126, v105
	v_mov_b32_e32 v127, v97
	v_pk_add_f32 v[118:119], v[118:119], v[124:125]
	v_mov_b32_e32 v124, v104
	v_mov_b32_e32 v125, v96
	v_pk_mul_f32 v[126:127], v[126:127], v[126:127]
	s_nop 0
	v_pk_fma_f32 v[124:125], v[124:125], v[124:125], v[126:127]
	v_mov_b32_e32 v126, v107
	v_mov_b32_e32 v127, v99
	v_pk_add_f32 v[118:119], v[118:119], v[124:125]
	v_mov_b32_e32 v124, v106
	v_mov_b32_e32 v125, v98
	v_pk_mul_f32 v[126:127], v[126:127], v[126:127]
	s_nop 0
	v_pk_fma_f32 v[124:125], v[124:125], v[124:125], v[126:127]
	s_nop 0
	v_pk_add_f32 v[118:119], v[124:125], v[118:119]
	v_cvt_pk_bf16_f32 v124, v177, v202
	v_cvt_pk_bf16_f32 v125, v196, v198
	v_cvt_pk_bf16_f32 v126, v199, v201
	v_cvt_pk_bf16_f32 v127, v203, v150
	ds_read_b32 v150, v189 offset:64
	v_add_f32_e32 v118, v118, v119
	v_mov_b32_e32 v119, v118
	s_nop 1
	v_permlane16_swap_b32_e32 v118, v119
	s_waitcnt lgkmcnt(0)
	v_add_f32_e32 v118, v118, v119
	v_mov_b32_e32 v119, v118
	s_nop 1
	v_permlane32_swap_b32_e32 v118, v119
	s_waitcnt lgkmcnt(0)
	v_add_f32_e32 v118, v118, v119
	v_mul_f32_e32 v118, v150, v118
	v_mul_f32_e32 v118, v150, v118
	v_fmamk_f32 v118, v118, 0x3c800000, v183
	v_mul_f32_e32 v119, 0x4f800000, v118
	v_cmp_gt_f32_e32 vcc, s92, v118
	s_nop 1
	v_cndmask_b32_e32 v177, v118, v119, vcc
	v_sqrt_f32_e32 v191, v177
	v_lshlrev_b64 v[118:119], 11, v[162:163]
	v_lshl_add_u64 v[118:119], v[164:165], 0, v[118:119]
	global_store_dwordx4 v[118:119], v[114:117], off
	global_store_dwordx4 v[118:119], v[124:127], off offset:64
	v_add_u32_e32 v163, -1, v191
	v_fma_f32 v196, -v163, v191, v177
	v_cmp_ge_f32_e64 s[4:5], 0, v196
	v_add_u32_e32 v196, 1, v191
	v_mov_b32_e32 v117, v108
	v_cndmask_b32_e64 v163, v191, v163, s[4:5]
	v_fma_f32 v191, -v196, v191, v177
	v_cmp_lt_f32_e64 s[4:5], 0, v191
	v_mov_b32_e32 v108, v105
	s_nop 0
	v_cndmask_b32_e64 v163, v163, v196, s[4:5]
	v_mul_f32_e32 v191, 0x37800000, v163
	v_cndmask_b32_e32 v163, v163, v191, vcc
	v_cmp_class_f32_e32 vcc, v177, v184
	s_nop 1
	v_cndmask_b32_e32 v163, v163, v177, vcc
	v_div_scale_f32 v177, s[4:5], v163, v163, v150
	v_rcp_f32_e32 v191, v177
	s_nop 0
	v_fma_f32 v114, -v177, v191, 1.0
	v_fmac_f32_e32 v191, v114, v191
	v_div_scale_f32 v114, vcc, v150, v163, v150
	v_mul_f32_e32 v115, v114, v191
	v_fma_f32 v116, -v177, v115, v114
	v_fmac_f32_e32 v115, v116, v191
	v_fma_f32 v114, -v177, v115, v114
	v_div_fmas_f32 v114, v114, v191, v115
	v_div_fixup_f32 v114, v114, v163, v150
	v_mov_b32_e32 v116, v104
	v_pk_mul_f32 v[116:117], v[116:117], v[114:115] op_sel_hi:[1,0]
	v_ashrrev_i32_e32 v177, 31, v176
	v_pk_mul_f32 v[116:117], v[174:175], v[116:117]
	s_waitcnt vmcnt(2)
	v_pk_mul_f32 v[118:119], v[192:193], v[116:117] op_sel:[0,1] op_sel_hi:[1,0]
	v_pk_mul_f32 v[116:117], v[192:193], v[116:117]
	v_sub_f32_e32 v115, v118, v119
	v_pk_mul_f32 v[104:105], v[108:109], v[114:115] op_sel_hi:[1,0]
	v_add_f32_e32 v116, v116, v117
	v_pk_mul_f32 v[104:105], v[172:173], v[104:105]
	s_nop 0
	v_pk_mul_f32 v[108:109], v[194:195], v[104:105] op_sel:[0,1] op_sel_hi:[1,0]
	v_pk_mul_f32 v[104:105], v[194:195], v[104:105]
	v_sub_f32_e32 v117, v108, v109
	v_add_f32_e32 v118, v104, v105
	v_mov_b32_e32 v104, v106
	v_mov_b32_e32 v105, v110
	v_pk_mul_f32 v[104:105], v[104:105], v[114:115] op_sel_hi:[1,0]
	v_mov_b32_e32 v110, v107
	v_pk_mul_f32 v[104:105], v[120:121], v[104:105]
	s_nop 0
	v_pk_mul_f32 v[108:109], v[136:137], v[104:105] op_sel:[0,1] op_sel_hi:[1,0]
	v_pk_mul_f32 v[104:105], v[136:137], v[104:105]
	v_sub_f32_e32 v108, v108, v109
	v_add_f32_e32 v109, v104, v105
	v_pk_mul_f32 v[104:105], v[110:111], v[114:115] op_sel_hi:[1,0]
	s_nop 0
	v_pk_mul_f32 v[104:105], v[170:171], v[104:105]
	s_nop 0
	v_pk_mul_f32 v[106:107], v[138:139], v[104:105] op_sel:[0,1] op_sel_hi:[1,0]
	v_pk_mul_f32 v[104:105], v[138:139], v[104:105]
	v_sub_f32_e32 v110, v106, v107
	v_add_f32_e32 v111, v104, v105
	v_mov_b32_e32 v105, v100
	v_mov_b32_e32 v100, v97
	v_mov_b32_e32 v104, v96
	v_pk_mul_f32 v[96:97], v[100:101], v[114:115] op_sel_hi:[1,0]
	v_pk_mul_f32 v[104:105], v[104:105], v[114:115] op_sel_hi:[1,0]
	v_pk_mul_f32 v[96:97], v[168:169], v[96:97]
	v_pk_mul_f32 v[104:105], v[122:123], v[104:105]
	v_pk_mul_f32 v[100:101], v[134:135], v[96:97] op_sel:[0,1] op_sel_hi:[1,0]
	v_pk_mul_f32 v[96:97], v[134:135], v[96:97]
	v_sub_f32_e32 v119, v100, v101
	v_add_f32_e32 v124, v96, v97
	v_mov_b32_e32 v96, v98
	v_mov_b32_e32 v97, v102
	v_pk_mul_f32 v[96:97], v[96:97], v[114:115] op_sel_hi:[1,0]
	v_mov_b32_e32 v102, v99
	v_pk_mul_f32 v[96:97], v[112:113], v[96:97]
	v_pk_mul_f32 v[106:107], v[132:133], v[104:105] op_sel:[0,1] op_sel_hi:[1,0]
	v_pk_mul_f32 v[100:101], v[128:129], v[96:97] op_sel:[0,1] op_sel_hi:[1,0]
	v_pk_mul_f32 v[96:97], v[128:129], v[96:97]
	v_sub_f32_e32 v106, v106, v107
	v_add_f32_e32 v125, v96, v97
	v_pk_mul_f32 v[96:97], v[102:103], v[114:115] op_sel_hi:[1,0]
	v_pk_mul_f32 v[104:105], v[132:133], v[104:105]
	v_pk_mul_f32 v[96:97], v[166:167], v[96:97]
	v_add_f32_e32 v107, v104, v105
	v_pk_mul_f32 v[98:99], v[130:131], v[96:97] op_sel:[0,1] op_sel_hi:[1,0]
	v_pk_mul_f32 v[96:97], v[130:131], v[96:97]
	v_sub_f32_e32 v99, v98, v99
	v_add_f32_e32 v103, v96, v97
	v_lshlrev_b64 v[96:97], 11, v[176:177]
	v_sub_f32_e32 v100, v100, v101
	v_lshl_add_u64 v[104:105], v[164:165], 0, v[96:97]
	v_cvt_pk_bf16_f32 v96, v115, v117
	v_cvt_pk_bf16_f32 v97, v108, v110
	v_cvt_pk_bf16_f32 v98, v106, v119
	v_cvt_pk_bf16_f32 v99, v100, v99
	v_or_b32_e32 v106, 32, v162
	v_cvt_pk_bf16_f32 v100, v116, v118
	v_cvt_pk_bf16_f32 v101, v109, v111
	v_cvt_pk_bf16_f32 v102, v107, v124
	v_cvt_pk_bf16_f32 v103, v125, v103
	global_store_dwordx4 v[104:105], v[96:99], off
	global_store_dwordx4 v[104:105], v[100:103], off offset:64
	v_or_b32_e32 v104, 48, v162
	v_lshlrev_b32_e32 v96, 8, v106
	v_and_b32_e32 v150, 0xfef00, v96
	v_lshl_add_u64 v[96:97], v[152:153], 0, v[150:151]
	global_load_dwordx4 v[108:111], v[96:97], off offset:16
	global_load_dwordx4 v[114:117], v[96:97], off
	global_load_dwordx4 v[124:127], v[96:97], off offset:32
	global_load_dwordx4 v[128:131], v[96:97], off offset:48
	v_mov_b32_e32 v100, v93
	v_mov_b32_e32 v101, v85
	v_mov_b32_e32 v98, v92
	v_mov_b32_e32 v99, v84
	v_pk_mul_f32 v[100:101], v[100:101], v[100:101]
	v_mov_b32_e32 v102, v95
	v_mov_b32_e32 v103, v87
	v_pk_fma_f32 v[98:99], v[98:99], v[98:99], v[100:101]
	v_mov_b32_e32 v100, v94
	v_mov_b32_e32 v101, v86
	v_pk_mul_f32 v[102:103], v[102:103], v[102:103]
	ds_read_b32 v105, v189 offset:128
	v_pk_fma_f32 v[100:101], v[100:101], v[100:101], v[102:103]
	v_mov_b32_e32 v102, v89
	v_mov_b32_e32 v103, v81
	v_pk_add_f32 v[98:99], v[98:99], v[100:101]
	v_mov_b32_e32 v100, v88
	v_mov_b32_e32 v101, v80
	v_pk_mul_f32 v[102:103], v[102:103], v[102:103]
	v_mov_b32_e32 v177, v92
	v_pk_fma_f32 v[100:101], v[100:101], v[100:101], v[102:103]
	v_mov_b32_e32 v102, v91
	v_mov_b32_e32 v103, v83
	v_pk_add_f32 v[98:99], v[98:99], v[100:101]
	v_mov_b32_e32 v100, v90
	v_mov_b32_e32 v101, v82
	v_pk_mul_f32 v[102:103], v[102:103], v[102:103]
	v_mov_b32_e32 v92, v89
	v_pk_fma_f32 v[100:101], v[100:101], v[100:101], v[102:103]
	s_nop 0
	v_pk_add_f32 v[98:99], v[100:101], v[98:99]
	s_nop 0
	v_add_f32_e32 v98, v98, v99
	v_mov_b32_e32 v99, v98
	s_nop 1
	v_permlane16_swap_b32_e32 v98, v99
	s_waitcnt lgkmcnt(0)
	v_add_f32_e32 v98, v98, v99
	v_mov_b32_e32 v99, v98
	s_nop 1
	v_permlane32_swap_b32_e32 v98, v99
	s_waitcnt lgkmcnt(0)
	v_add_f32_e32 v96, v98, v99
	v_mul_f32_e32 v96, v105, v96
	v_mul_f32_e32 v96, v105, v96
	v_fmamk_f32 v96, v96, 0x3c800000, v183
	v_mul_f32_e32 v97, 0x4f800000, v96
	v_cmp_gt_f32_e32 vcc, s92, v96
	v_lshlrev_b32_e32 v98, 8, v104
	v_and_b32_e32 v150, 0xfff00, v98
	v_cndmask_b32_e32 v96, v96, v97, vcc
	v_sqrt_f32_e32 v97, v96
	v_lshl_add_u64 v[118:119], v[152:153], 0, v[150:151]
	v_add_u32_e32 v98, -1, v97
	v_fma_f32 v99, -v98, v97, v96
	v_cmp_ge_f32_e64 s[4:5], 0, v99
	v_add_u32_e32 v99, 1, v97
	s_nop 0
	v_cndmask_b32_e64 v98, v97, v98, s[4:5]
	v_fma_f32 v97, -v99, v97, v96
	v_cmp_lt_f32_e64 s[4:5], 0, v97
	s_nop 1
	v_cndmask_b32_e64 v97, v98, v99, s[4:5]
	v_mul_f32_e32 v98, 0x37800000, v97
	v_cndmask_b32_e32 v97, v97, v98, vcc
	v_cmp_class_f32_e32 vcc, v96, v184
	s_nop 1
	v_cndmask_b32_e32 v107, v97, v96, vcc
	v_div_scale_f32 v150, s[4:5], v107, v107, v105
	v_rcp_f32_e32 v163, v150
	global_load_dwordx4 v[96:99], v[118:119], off offset:48
	global_load_dwordx4 v[100:103], v[118:119], off offset:32
	global_load_dwordx4 v[132:135], v[118:119], off offset:16
	global_load_dwordx4 v[136:139], v[118:119], off
	v_fma_f32 v118, -v150, v163, 1.0
	v_fmac_f32_e32 v163, v118, v163
	v_div_scale_f32 v118, vcc, v105, v107, v105
	v_mul_f32_e32 v119, v118, v163
	v_fma_f32 v176, -v150, v119, v118
	v_fmac_f32_e32 v119, v176, v163
	v_fma_f32 v118, -v150, v119, v118
	v_div_fmas_f32 v118, v118, v163, v119
	v_div_fixup_f32 v118, v118, v107, v105
	v_mov_b32_e32 v176, v88
	v_pk_mul_f32 v[176:177], v[176:177], v[118:119] op_sel_hi:[1,0]
	v_pk_mul_f32 v[88:89], v[92:93], v[118:119] op_sel_hi:[1,0]
	v_pk_mul_f32 v[176:177], v[174:175], v[176:177]
	v_pk_mul_f32 v[88:89], v[172:173], v[88:89]
	s_waitcnt vmcnt(6)
	v_pk_mul_f32 v[192:193], v[114:115], v[176:177] op_sel:[0,1] op_sel_hi:[1,0]
	v_pk_mul_f32 v[114:115], v[114:115], v[176:177]
	v_pk_mul_f32 v[92:93], v[116:117], v[88:89] op_sel:[0,1] op_sel_hi:[1,0]
	v_pk_mul_f32 v[88:89], v[116:117], v[88:89]
	v_add_f32_e32 v107, v114, v115
	v_add_f32_e32 v115, v88, v89
	v_mov_b32_e32 v88, v90
	v_mov_b32_e32 v89, v94
	v_pk_mul_f32 v[88:89], v[88:89], v[118:119] op_sel_hi:[1,0]
	v_sub_f32_e32 v114, v92, v93
	v_pk_mul_f32 v[88:89], v[120:121], v[88:89]
	v_mov_b32_e32 v94, v91
	v_pk_mul_f32 v[92:93], v[108:109], v[88:89] op_sel:[0,1] op_sel_hi:[1,0]
	v_pk_mul_f32 v[88:89], v[108:109], v[88:89]
	v_sub_f32_e32 v92, v92, v93
	v_add_f32_e32 v93, v88, v89
	v_pk_mul_f32 v[88:89], v[94:95], v[118:119] op_sel_hi:[1,0]
	v_sub_f32_e32 v105, v192, v193
	v_pk_mul_f32 v[88:89], v[170:171], v[88:89]
	s_nop 0
	v_pk_mul_f32 v[90:91], v[110:111], v[88:89] op_sel:[0,1] op_sel_hi:[1,0]
	v_pk_mul_f32 v[88:89], v[110:111], v[88:89]
	v_sub_f32_e32 v94, v90, v91
	v_add_f32_e32 v95, v88, v89
	v_mov_b32_e32 v89, v84
	v_mov_b32_e32 v84, v81
	v_mov_b32_e32 v88, v80
	v_pk_mul_f32 v[80:81], v[84:85], v[118:119] op_sel_hi:[1,0]
	v_pk_mul_f32 v[88:89], v[88:89], v[118:119] op_sel_hi:[1,0]
	v_pk_mul_f32 v[80:81], v[168:169], v[80:81]
	v_pk_mul_f32 v[88:89], v[122:123], v[88:89]
	s_waitcnt vmcnt(5)
	v_pk_mul_f32 v[84:85], v[126:127], v[80:81] op_sel:[0,1] op_sel_hi:[1,0]
	v_pk_mul_f32 v[80:81], v[126:127], v[80:81]
	v_pk_mul_f32 v[90:91], v[124:125], v[88:89] op_sel:[0,1] op_sel_hi:[1,0]
	v_add_f32_e32 v108, v80, v81
	v_mov_b32_e32 v80, v82
	v_mov_b32_e32 v81, v86
	v_pk_mul_f32 v[80:81], v[80:81], v[118:119] op_sel_hi:[1,0]
	v_pk_mul_f32 v[88:89], v[124:125], v[88:89]
	v_pk_mul_f32 v[80:81], v[112:113], v[80:81]
	v_sub_f32_e32 v90, v90, v91
	v_add_f32_e32 v91, v88, v89
	v_sub_f32_e32 v88, v84, v85
	s_waitcnt vmcnt(4)
	v_pk_mul_f32 v[84:85], v[128:129], v[80:81] op_sel:[0,1] op_sel_hi:[1,0]
	v_pk_mul_f32 v[80:81], v[128:129], v[80:81]
	v_mov_b32_e32 v86, v83
	v_add_f32_e32 v109, v80, v81
	v_pk_mul_f32 v[80:81], v[86:87], v[118:119] op_sel_hi:[1,0]
	v_sub_f32_e32 v84, v84, v85
	v_pk_mul_f32 v[80:81], v[166:167], v[80:81]
	v_mov_b32_e32 v86, v77
	v_pk_mul_f32 v[82:83], v[130:131], v[80:81] op_sel:[0,1] op_sel_hi:[1,0]
	v_pk_mul_f32 v[80:81], v[130:131], v[80:81]
	v_sub_f32_e32 v83, v82, v83
	v_mov_b32_e32 v87, v69
	v_add_f32_e32 v110, v80, v81
	v_cvt_pk_bf16_f32 v80, v105, v114
	v_cvt_pk_bf16_f32 v81, v92, v94
	v_cvt_pk_bf16_f32 v82, v90, v88
	v_cvt_pk_bf16_f32 v83, v84, v83
	v_mov_b32_e32 v84, v76
	v_mov_b32_e32 v85, v68
	v_pk_mul_f32 v[86:87], v[86:87], v[86:87]
	v_mov_b32_e32 v88, v79
	v_mov_b32_e32 v89, v71
	v_pk_fma_f32 v[84:85], v[84:85], v[84:85], v[86:87]
	v_mov_b32_e32 v86, v78
	v_mov_b32_e32 v87, v70
	v_pk_mul_f32 v[88:89], v[88:89], v[88:89]
	v_ashrrev_i32_e32 v105, 31, v104
	v_pk_fma_f32 v[86:87], v[86:87], v[86:87], v[88:89]
	v_mov_b32_e32 v88, v73
	v_mov_b32_e32 v89, v65
	v_pk_add_f32 v[84:85], v[84:85], v[86:87]
	v_mov_b32_e32 v86, v72
	v_mov_b32_e32 v87, v64
	v_pk_mul_f32 v[88:89], v[88:89], v[88:89]
	s_nop 0
	v_pk_fma_f32 v[86:87], v[86:87], v[86:87], v[88:89]
	v_mov_b32_e32 v88, v75
	v_mov_b32_e32 v89, v67
	v_pk_add_f32 v[84:85], v[84:85], v[86:87]
	v_mov_b32_e32 v86, v74
	v_mov_b32_e32 v87, v66
	v_pk_mul_f32 v[88:89], v[88:89], v[88:89]
	s_nop 0
	v_pk_fma_f32 v[86:87], v[86:87], v[86:87], v[88:89]
	s_nop 0
	v_pk_add_f32 v[84:85], v[86:87], v[84:85]
	s_nop 0
	v_add_f32_e32 v88, v84, v85
	v_mov_b32_e32 v89, v88
	s_nop 1
	v_permlane16_swap_b32_e32 v88, v89
	v_cvt_pk_bf16_f32 v84, v107, v115
	v_cvt_pk_bf16_f32 v85, v93, v95
	v_cvt_pk_bf16_f32 v86, v91, v108
	v_cvt_pk_bf16_f32 v87, v109, v110
	s_waitcnt lgkmcnt(0)
	v_add_f32_e32 v88, v88, v89
	v_mov_b32_e32 v89, v88
	s_nop 1
	v_permlane32_swap_b32_e32 v88, v89
	ds_read_b32 v90, v189 offset:192
	v_ashrrev_i32_e32 v107, 31, v106
	s_waitcnt lgkmcnt(1)
	v_add_f32_e32 v88, v88, v89
	s_waitcnt lgkmcnt(0)
	v_mul_f32_e32 v88, v90, v88
	v_mul_f32_e32 v88, v90, v88
	v_fmamk_f32 v88, v88, 0x3c800000, v183
	v_mul_f32_e32 v89, 0x4f800000, v88
	v_cmp_gt_f32_e32 vcc, s92, v88
	s_nop 1
	v_cndmask_b32_e32 v91, v88, v89, vcc
	v_sqrt_f32_e32 v92, v91
	v_lshlrev_b64 v[88:89], 11, v[106:107]
	v_lshl_add_u64 v[88:89], v[164:165], 0, v[88:89]
	global_store_dwordx4 v[88:89], v[80:83], off
	global_store_dwordx4 v[88:89], v[84:87], off offset:64
	v_add_u32_e32 v93, -1, v92
	v_fma_f32 v94, -v93, v92, v91
	v_cmp_ge_f32_e64 s[4:5], 0, v94
	v_add_u32_e32 v94, 1, v92
	v_mov_b32_e32 v83, v76
	v_cndmask_b32_e64 v93, v92, v93, s[4:5]
	v_fma_f32 v92, -v94, v92, v91
	v_cmp_lt_f32_e64 s[4:5], 0, v92
	v_mov_b32_e32 v76, v73
	s_nop 0
	v_cndmask_b32_e64 v92, v93, v94, s[4:5]
	v_mul_f32_e32 v93, 0x37800000, v92
	v_cndmask_b32_e32 v92, v92, v93, vcc
	v_cmp_class_f32_e32 vcc, v91, v184
	s_nop 1
	v_cndmask_b32_e32 v91, v92, v91, vcc
	v_div_scale_f32 v92, s[4:5], v91, v91, v90
	v_rcp_f32_e32 v93, v92
	s_nop 0
	v_fma_f32 v80, -v92, v93, 1.0
	v_fmac_f32_e32 v93, v80, v93
	v_div_scale_f32 v80, vcc, v90, v91, v90
	v_mul_f32_e32 v81, v80, v93
	v_fma_f32 v82, -v92, v81, v80
	v_fmac_f32_e32 v81, v82, v93
	v_fma_f32 v80, -v92, v81, v80
	v_div_fmas_f32 v80, v80, v93, v81
	v_div_fixup_f32 v80, v80, v91, v90
	v_mov_b32_e32 v82, v72
	v_pk_mul_f32 v[82:83], v[82:83], v[80:81] op_sel_hi:[1,0]
	s_nop 0
	v_pk_mul_f32 v[82:83], v[174:175], v[82:83]
	s_waitcnt vmcnt(2)
	v_pk_mul_f32 v[84:85], v[136:137], v[82:83] op_sel:[0,1] op_sel_hi:[1,0]
	v_pk_mul_f32 v[82:83], v[136:137], v[82:83]
	v_sub_f32_e32 v81, v84, v85
	v_pk_mul_f32 v[72:73], v[76:77], v[80:81] op_sel_hi:[1,0]
	v_add_f32_e32 v82, v82, v83
	v_pk_mul_f32 v[72:73], v[172:173], v[72:73]
	s_nop 0
	v_pk_mul_f32 v[76:77], v[138:139], v[72:73] op_sel:[0,1] op_sel_hi:[1,0]
	v_pk_mul_f32 v[72:73], v[138:139], v[72:73]
	v_sub_f32_e32 v83, v76, v77
	v_add_f32_e32 v84, v72, v73
	v_mov_b32_e32 v72, v74
	v_mov_b32_e32 v73, v78
	v_pk_mul_f32 v[72:73], v[72:73], v[80:81] op_sel_hi:[1,0]
	v_mov_b32_e32 v78, v75
	v_pk_mul_f32 v[72:73], v[120:121], v[72:73]
	s_nop 0
	v_pk_mul_f32 v[76:77], v[132:133], v[72:73] op_sel:[0,1] op_sel_hi:[1,0]
	v_pk_mul_f32 v[72:73], v[132:133], v[72:73]
	v_sub_f32_e32 v76, v76, v77
	v_add_f32_e32 v77, v72, v73
	v_pk_mul_f32 v[72:73], v[78:79], v[80:81] op_sel_hi:[1,0]
	s_nop 0
	v_pk_mul_f32 v[72:73], v[170:171], v[72:73]
	s_nop 0
	v_pk_mul_f32 v[74:75], v[134:135], v[72:73] op_sel:[0,1] op_sel_hi:[1,0]
	v_pk_mul_f32 v[72:73], v[134:135], v[72:73]
	v_sub_f32_e32 v78, v74, v75
	v_add_f32_e32 v79, v72, v73
	v_mov_b32_e32 v73, v68
	v_mov_b32_e32 v68, v65
	v_mov_b32_e32 v72, v64
	v_pk_mul_f32 v[64:65], v[68:69], v[80:81] op_sel_hi:[1,0]
	v_pk_mul_f32 v[72:73], v[72:73], v[80:81] op_sel_hi:[1,0]
	v_pk_mul_f32 v[64:65], v[168:169], v[64:65]
	v_pk_mul_f32 v[72:73], v[122:123], v[72:73]
	v_pk_mul_f32 v[68:69], v[102:103], v[64:65] op_sel:[0,1] op_sel_hi:[1,0]
	v_pk_mul_f32 v[64:65], v[102:103], v[64:65]
	v_sub_f32_e32 v85, v68, v69
	v_add_f32_e32 v86, v64, v65
	v_mov_b32_e32 v64, v66
	v_mov_b32_e32 v65, v70
	v_pk_mul_f32 v[64:65], v[64:65], v[80:81] op_sel_hi:[1,0]
	v_mov_b32_e32 v70, v67
	v_pk_mul_f32 v[64:65], v[112:113], v[64:65]
	v_pk_mul_f32 v[74:75], v[100:101], v[72:73] op_sel:[0,1] op_sel_hi:[1,0]
	v_pk_mul_f32 v[68:69], v[96:97], v[64:65] op_sel:[0,1] op_sel_hi:[1,0]
	v_pk_mul_f32 v[64:65], v[96:97], v[64:65]
	v_sub_f32_e32 v74, v74, v75
	v_add_f32_e32 v87, v64, v65
	v_pk_mul_f32 v[64:65], v[70:71], v[80:81] op_sel_hi:[1,0]
	v_pk_mul_f32 v[72:73], v[100:101], v[72:73]
	v_pk_mul_f32 v[64:65], v[166:167], v[64:65]
	v_add_f32_e32 v75, v72, v73
	v_pk_mul_f32 v[66:67], v[98:99], v[64:65] op_sel:[0,1] op_sel_hi:[1,0]
	v_pk_mul_f32 v[64:65], v[98:99], v[64:65]
	v_sub_f32_e32 v67, v66, v67
	v_add_f32_e32 v71, v64, v65
	v_lshlrev_b64 v[64:65], 11, v[104:105]
	v_sub_f32_e32 v68, v68, v69
	v_lshl_add_u64 v[72:73], v[164:165], 0, v[64:65]
	v_cvt_pk_bf16_f32 v64, v81, v83
	v_cvt_pk_bf16_f32 v65, v76, v78
	v_cvt_pk_bf16_f32 v66, v74, v85
	v_cvt_pk_bf16_f32 v67, v68, v67
	v_add_u32_e32 v74, 0x80, v162
	v_cvt_pk_bf16_f32 v68, v82, v84
	v_cvt_pk_bf16_f32 v69, v77, v79
	v_cvt_pk_bf16_f32 v70, v75, v86
	v_cvt_pk_bf16_f32 v71, v87, v71
	global_store_dwordx4 v[72:73], v[64:67], off
	global_store_dwordx4 v[72:73], v[68:71], off offset:64
	v_add_u32_e32 v72, 0x90, v162
	v_lshlrev_b32_e32 v64, 8, v74
	v_and_b32_e32 v150, 0xfcf00, v64
	v_lshl_add_u64 v[64:65], v[152:153], 0, v[150:151]
	global_load_dwordx4 v[76:79], v[64:65], off offset:16
	global_load_dwordx4 v[80:83], v[64:65], off
	global_load_dwordx4 v[84:87], v[64:65], off offset:32
	global_load_dwordx4 v[88:91], v[64:65], off offset:48
	v_mov_b32_e32 v68, v61
	v_mov_b32_e32 v69, v53
	v_mov_b32_e32 v66, v60
	v_mov_b32_e32 v67, v52
	v_pk_mul_f32 v[68:69], v[68:69], v[68:69]
	v_mov_b32_e32 v70, v63
	v_mov_b32_e32 v71, v55
	v_pk_fma_f32 v[66:67], v[66:67], v[66:67], v[68:69]
	v_mov_b32_e32 v68, v62
	v_mov_b32_e32 v69, v54
	v_pk_mul_f32 v[70:71], v[70:71], v[70:71]
	ds_read_b32 v73, v189 offset:512
	v_pk_fma_f32 v[68:69], v[68:69], v[68:69], v[70:71]
	v_mov_b32_e32 v70, v57
	v_mov_b32_e32 v71, v49
	v_pk_add_f32 v[66:67], v[66:67], v[68:69]
	v_mov_b32_e32 v68, v56
	v_mov_b32_e32 v69, v48
	v_pk_mul_f32 v[70:71], v[70:71], v[70:71]
	s_nop 0
	v_pk_fma_f32 v[68:69], v[68:69], v[68:69], v[70:71]
	v_mov_b32_e32 v70, v59
	v_mov_b32_e32 v71, v51
	v_pk_add_f32 v[66:67], v[66:67], v[68:69]
	v_mov_b32_e32 v68, v58
	v_mov_b32_e32 v69, v50
	v_pk_mul_f32 v[70:71], v[70:71], v[70:71]
	s_nop 0
	v_pk_fma_f32 v[68:69], v[68:69], v[68:69], v[70:71]
	s_nop 0
	v_pk_add_f32 v[66:67], v[68:69], v[66:67]
	s_nop 0
	v_add_f32_e32 v66, v66, v67
	v_mov_b32_e32 v67, v66
	s_nop 1
	v_permlane16_swap_b32_e32 v66, v67
	s_waitcnt lgkmcnt(0)
	v_add_f32_e32 v66, v66, v67
	v_mov_b32_e32 v67, v66
	s_nop 1
	v_permlane32_swap_b32_e32 v66, v67
	s_waitcnt lgkmcnt(0)
	v_add_f32_e32 v64, v66, v67
	v_mul_f32_e32 v64, v73, v64
	v_mul_f32_e32 v64, v73, v64
	v_fmamk_f32 v64, v64, 0x3c800000, v183
	v_mul_f32_e32 v65, 0x4f800000, v64
	v_cmp_gt_f32_e32 vcc, s92, v64
	v_lshlrev_b32_e32 v66, 8, v72
	v_and_b32_e32 v150, 0xfdf00, v66
	v_cndmask_b32_e32 v64, v64, v65, vcc
	v_sqrt_f32_e32 v65, v64
	v_lshl_add_u64 v[96:97], v[152:153], 0, v[150:151]
	v_add_u32_e32 v66, -1, v65
	v_fma_f32 v67, -v66, v65, v64
	v_cmp_ge_f32_e64 s[4:5], 0, v67
	v_add_u32_e32 v67, 1, v65
	s_nop 0
	v_cndmask_b32_e64 v66, v65, v66, s[4:5]
	v_fma_f32 v65, -v67, v65, v64
	v_cmp_lt_f32_e64 s[4:5], 0, v65
	s_nop 1
	v_cndmask_b32_e64 v65, v66, v67, s[4:5]
	v_mul_f32_e32 v66, 0x37800000, v65
	v_cndmask_b32_e32 v65, v65, v66, vcc
	v_cmp_class_f32_e32 vcc, v64, v184
	s_nop 1
	v_cndmask_b32_e32 v75, v65, v64, vcc
	v_div_scale_f32 v100, s[4:5], v75, v75, v73
	v_rcp_f32_e32 v101, v100
	global_load_dwordx4 v[64:67], v[96:97], off offset:48
	global_load_dwordx4 v[68:71], v[96:97], off offset:32
	global_load_dwordx4 v[92:95], v[96:97], off offset:16
	s_nop 0
	global_load_dwordx4 v[96:99], v[96:97], off
	v_fma_f32 v102, -v100, v101, 1.0
	v_fmac_f32_e32 v101, v102, v101
	v_div_scale_f32 v102, vcc, v73, v75, v73
	v_mul_f32_e32 v103, v102, v101
	v_fma_f32 v104, -v100, v103, v102
	v_fmac_f32_e32 v103, v104, v101
	v_fma_f32 v100, -v100, v103, v102
	v_div_fmas_f32 v100, v100, v101, v103
	v_div_fixup_f32 v100, v100, v75, v73
	v_mov_b32_e32 v102, v56
	v_mov_b32_e32 v103, v60
	v_mov_b32_e32 v60, v57
	v_pk_mul_f32 v[102:103], v[102:103], v[100:101] op_sel_hi:[1,0]
	v_pk_mul_f32 v[56:57], v[60:61], v[100:101] op_sel_hi:[1,0]
	v_pk_mul_f32 v[102:103], v[174:175], v[102:103]
	v_pk_mul_f32 v[56:57], v[172:173], v[56:57]
	s_waitcnt vmcnt(6)
	v_pk_mul_f32 v[104:105], v[80:81], v[102:103] op_sel:[0,1] op_sel_hi:[1,0]
	v_pk_mul_f32 v[80:81], v[80:81], v[102:103]
	v_pk_mul_f32 v[60:61], v[82:83], v[56:57] op_sel:[0,1] op_sel_hi:[1,0]
	v_pk_mul_f32 v[56:57], v[82:83], v[56:57]
	v_add_f32_e32 v75, v80, v81
	v_add_f32_e32 v81, v56, v57
	v_mov_b32_e32 v56, v58
	v_mov_b32_e32 v57, v62
	v_pk_mul_f32 v[56:57], v[56:57], v[100:101] op_sel_hi:[1,0]
	v_sub_f32_e32 v80, v60, v61
	v_pk_mul_f32 v[56:57], v[120:121], v[56:57]
	v_mov_b32_e32 v62, v59
	v_pk_mul_f32 v[60:61], v[76:77], v[56:57] op_sel:[0,1] op_sel_hi:[1,0]
	v_pk_mul_f32 v[56:57], v[76:77], v[56:57]
	v_sub_f32_e32 v60, v60, v61
	v_add_f32_e32 v61, v56, v57
	v_pk_mul_f32 v[56:57], v[62:63], v[100:101] op_sel_hi:[1,0]
	v_sub_f32_e32 v73, v104, v105
	v_pk_mul_f32 v[56:57], v[170:171], v[56:57]
	s_nop 0
	v_pk_mul_f32 v[58:59], v[78:79], v[56:57] op_sel:[0,1] op_sel_hi:[1,0]
	v_pk_mul_f32 v[56:57], v[78:79], v[56:57]
	v_sub_f32_e32 v62, v58, v59
	v_add_f32_e32 v63, v56, v57
	v_mov_b32_e32 v57, v52
	v_mov_b32_e32 v52, v49
	v_mov_b32_e32 v56, v48
	v_pk_mul_f32 v[48:49], v[52:53], v[100:101] op_sel_hi:[1,0]
	v_pk_mul_f32 v[56:57], v[56:57], v[100:101] op_sel_hi:[1,0]
	v_pk_mul_f32 v[48:49], v[168:169], v[48:49]
	v_pk_mul_f32 v[56:57], v[122:123], v[56:57]
	s_waitcnt vmcnt(5)
	v_pk_mul_f32 v[52:53], v[86:87], v[48:49] op_sel:[0,1] op_sel_hi:[1,0]
	v_pk_mul_f32 v[48:49], v[86:87], v[48:49]
	v_pk_mul_f32 v[58:59], v[84:85], v[56:57] op_sel:[0,1] op_sel_hi:[1,0]
	v_add_f32_e32 v76, v48, v49
	v_mov_b32_e32 v48, v50
	v_mov_b32_e32 v49, v54
	v_pk_mul_f32 v[48:49], v[48:49], v[100:101] op_sel_hi:[1,0]
	v_pk_mul_f32 v[56:57], v[84:85], v[56:57]
	v_pk_mul_f32 v[48:49], v[112:113], v[48:49]
	v_sub_f32_e32 v58, v58, v59
	v_add_f32_e32 v59, v56, v57
	v_sub_f32_e32 v56, v52, v53
	s_waitcnt vmcnt(4)
	v_pk_mul_f32 v[52:53], v[88:89], v[48:49] op_sel:[0,1] op_sel_hi:[1,0]
	v_pk_mul_f32 v[48:49], v[88:89], v[48:49]
	v_mov_b32_e32 v54, v51
	v_add_f32_e32 v77, v48, v49
	v_pk_mul_f32 v[48:49], v[54:55], v[100:101] op_sel_hi:[1,0]
	v_sub_f32_e32 v52, v52, v53
	v_pk_mul_f32 v[48:49], v[166:167], v[48:49]
	v_mov_b32_e32 v54, v45
	v_pk_mul_f32 v[50:51], v[90:91], v[48:49] op_sel:[0,1] op_sel_hi:[1,0]
	v_pk_mul_f32 v[48:49], v[90:91], v[48:49]
	v_sub_f32_e32 v51, v50, v51
	v_mov_b32_e32 v55, v37
	v_add_f32_e32 v78, v48, v49
	v_cvt_pk_bf16_f32 v48, v73, v80
	v_cvt_pk_bf16_f32 v49, v60, v62
	v_cvt_pk_bf16_f32 v50, v58, v56
	v_cvt_pk_bf16_f32 v51, v52, v51
	v_mov_b32_e32 v52, v44
	v_mov_b32_e32 v53, v36
	v_pk_mul_f32 v[54:55], v[54:55], v[54:55]
	v_mov_b32_e32 v56, v47
	v_mov_b32_e32 v57, v39
	v_pk_fma_f32 v[52:53], v[52:53], v[52:53], v[54:55]
	v_mov_b32_e32 v54, v46
	v_mov_b32_e32 v55, v38
	v_pk_mul_f32 v[56:57], v[56:57], v[56:57]
	v_ashrrev_i32_e32 v73, 31, v72
	v_pk_fma_f32 v[54:55], v[54:55], v[54:55], v[56:57]
	v_mov_b32_e32 v56, v41
	v_mov_b32_e32 v57, v33
	v_pk_add_f32 v[52:53], v[52:53], v[54:55]
	v_mov_b32_e32 v54, v40
	v_mov_b32_e32 v55, v32
	v_pk_mul_f32 v[56:57], v[56:57], v[56:57]
	s_nop 0
	v_pk_fma_f32 v[54:55], v[54:55], v[54:55], v[56:57]
	v_mov_b32_e32 v56, v43
	v_mov_b32_e32 v57, v35
	v_pk_add_f32 v[52:53], v[52:53], v[54:55]
	v_mov_b32_e32 v54, v42
	v_mov_b32_e32 v55, v34
	v_pk_mul_f32 v[56:57], v[56:57], v[56:57]
	s_nop 0
	v_pk_fma_f32 v[54:55], v[54:55], v[54:55], v[56:57]
	s_nop 0
	v_pk_add_f32 v[52:53], v[54:55], v[52:53]
	s_nop 0
	v_add_f32_e32 v56, v52, v53
	v_mov_b32_e32 v57, v56
	s_nop 1
	v_permlane16_swap_b32_e32 v56, v57
	v_cvt_pk_bf16_f32 v52, v75, v81
	v_cvt_pk_bf16_f32 v53, v61, v63
	v_cvt_pk_bf16_f32 v54, v59, v76
	v_cvt_pk_bf16_f32 v55, v77, v78
	s_waitcnt lgkmcnt(0)
	v_add_f32_e32 v56, v56, v57
	v_mov_b32_e32 v57, v56
	s_nop 1
	v_permlane32_swap_b32_e32 v56, v57
	ds_read_b32 v58, v189 offset:576
	v_ashrrev_i32_e32 v75, 31, v74
	s_waitcnt lgkmcnt(1)
	v_add_f32_e32 v56, v56, v57
	s_waitcnt lgkmcnt(0)
	v_mul_f32_e32 v56, v58, v56
	v_mul_f32_e32 v56, v58, v56
	v_fmamk_f32 v56, v56, 0x3c800000, v183
	v_mul_f32_e32 v57, 0x4f800000, v56
	v_cmp_gt_f32_e32 vcc, s92, v56
	s_nop 1
	v_cndmask_b32_e32 v59, v56, v57, vcc
	v_sqrt_f32_e32 v60, v59
	v_lshlrev_b64 v[56:57], 11, v[74:75]
	v_lshl_add_u64 v[56:57], v[164:165], 0, v[56:57]
	global_store_dwordx4 v[56:57], v[48:51], off
	global_store_dwordx4 v[56:57], v[52:55], off offset:64
	v_add_u32_e32 v61, -1, v60
	v_fma_f32 v62, -v61, v60, v59
	v_cmp_ge_f32_e64 s[4:5], 0, v62
	v_add_u32_e32 v62, 1, v60
	v_mov_b32_e32 v51, v44
	v_cndmask_b32_e64 v61, v60, v61, s[4:5]
	v_fma_f32 v60, -v62, v60, v59
	v_cmp_lt_f32_e64 s[4:5], 0, v60
	v_mov_b32_e32 v44, v41
	s_nop 0
	v_cndmask_b32_e64 v60, v61, v62, s[4:5]
	v_mul_f32_e32 v61, 0x37800000, v60
	v_cndmask_b32_e32 v60, v60, v61, vcc
	v_cmp_class_f32_e32 vcc, v59, v184
	s_nop 1
	v_cndmask_b32_e32 v59, v60, v59, vcc
	v_div_scale_f32 v60, s[4:5], v59, v59, v58
	v_rcp_f32_e32 v61, v60
	s_nop 0
	v_fma_f32 v48, -v60, v61, 1.0
	v_fmac_f32_e32 v61, v48, v61
	v_div_scale_f32 v48, vcc, v58, v59, v58
	v_mul_f32_e32 v49, v48, v61
	v_fma_f32 v50, -v60, v49, v48
	v_fmac_f32_e32 v49, v50, v61
	v_fma_f32 v48, -v60, v49, v48
	v_div_fmas_f32 v48, v48, v61, v49
	v_div_fixup_f32 v48, v48, v59, v58
	v_mov_b32_e32 v50, v40
	v_pk_mul_f32 v[50:51], v[50:51], v[48:49] op_sel_hi:[1,0]
	s_nop 0
	v_pk_mul_f32 v[50:51], v[174:175], v[50:51]
	s_waitcnt vmcnt(2)
	v_pk_mul_f32 v[52:53], v[96:97], v[50:51] op_sel:[0,1] op_sel_hi:[1,0]
	v_pk_mul_f32 v[50:51], v[96:97], v[50:51]
	v_sub_f32_e32 v49, v52, v53
	v_pk_mul_f32 v[40:41], v[44:45], v[48:49] op_sel_hi:[1,0]
	v_add_f32_e32 v50, v50, v51
	v_pk_mul_f32 v[40:41], v[172:173], v[40:41]
	s_nop 0
	v_pk_mul_f32 v[44:45], v[98:99], v[40:41] op_sel:[0,1] op_sel_hi:[1,0]
	v_pk_mul_f32 v[40:41], v[98:99], v[40:41]
	v_sub_f32_e32 v51, v44, v45
	v_add_f32_e32 v52, v40, v41
	v_mov_b32_e32 v40, v42
	v_mov_b32_e32 v41, v46
	v_pk_mul_f32 v[40:41], v[40:41], v[48:49] op_sel_hi:[1,0]
	v_mov_b32_e32 v46, v43
	v_pk_mul_f32 v[40:41], v[120:121], v[40:41]
	s_nop 0
	v_pk_mul_f32 v[44:45], v[92:93], v[40:41] op_sel:[0,1] op_sel_hi:[1,0]
	v_pk_mul_f32 v[40:41], v[92:93], v[40:41]
	v_sub_f32_e32 v44, v44, v45
	v_add_f32_e32 v45, v40, v41
	v_pk_mul_f32 v[40:41], v[46:47], v[48:49] op_sel_hi:[1,0]
	s_nop 0
	v_pk_mul_f32 v[40:41], v[170:171], v[40:41]
	s_nop 0
	v_pk_mul_f32 v[42:43], v[94:95], v[40:41] op_sel:[0,1] op_sel_hi:[1,0]
	v_pk_mul_f32 v[40:41], v[94:95], v[40:41]
	v_sub_f32_e32 v46, v42, v43
	v_add_f32_e32 v47, v40, v41
	v_mov_b32_e32 v41, v36
	v_mov_b32_e32 v36, v33
	v_mov_b32_e32 v40, v32
	v_pk_mul_f32 v[32:33], v[36:37], v[48:49] op_sel_hi:[1,0]
	v_pk_mul_f32 v[40:41], v[40:41], v[48:49] op_sel_hi:[1,0]
	v_pk_mul_f32 v[32:33], v[168:169], v[32:33]
	v_pk_mul_f32 v[40:41], v[122:123], v[40:41]
	v_pk_mul_f32 v[36:37], v[70:71], v[32:33] op_sel:[0,1] op_sel_hi:[1,0]
	v_pk_mul_f32 v[32:33], v[70:71], v[32:33]
	v_sub_f32_e32 v53, v36, v37
	v_add_f32_e32 v54, v32, v33
	v_mov_b32_e32 v32, v34
	v_mov_b32_e32 v33, v38
	v_pk_mul_f32 v[32:33], v[32:33], v[48:49] op_sel_hi:[1,0]
	v_mov_b32_e32 v38, v35
	v_pk_mul_f32 v[32:33], v[112:113], v[32:33]
	v_pk_mul_f32 v[42:43], v[68:69], v[40:41] op_sel:[0,1] op_sel_hi:[1,0]
	v_pk_mul_f32 v[36:37], v[64:65], v[32:33] op_sel:[0,1] op_sel_hi:[1,0]
	v_pk_mul_f32 v[32:33], v[64:65], v[32:33]
	v_sub_f32_e32 v42, v42, v43
	v_add_f32_e32 v55, v32, v33
	v_pk_mul_f32 v[32:33], v[38:39], v[48:49] op_sel_hi:[1,0]
	v_pk_mul_f32 v[40:41], v[68:69], v[40:41]
	v_pk_mul_f32 v[32:33], v[166:167], v[32:33]
	v_add_f32_e32 v43, v40, v41
	v_pk_mul_f32 v[34:35], v[66:67], v[32:33] op_sel:[0,1] op_sel_hi:[1,0]
	v_pk_mul_f32 v[32:33], v[66:67], v[32:33]
	v_sub_f32_e32 v35, v34, v35
	v_add_f32_e32 v39, v32, v33
	v_lshlrev_b64 v[32:33], 11, v[72:73]
	v_sub_f32_e32 v36, v36, v37
	v_lshl_add_u64 v[40:41], v[164:165], 0, v[32:33]
	v_cvt_pk_bf16_f32 v32, v49, v51
	v_cvt_pk_bf16_f32 v33, v44, v46
	v_cvt_pk_bf16_f32 v34, v42, v53
	v_cvt_pk_bf16_f32 v35, v36, v35
	v_add_u32_e32 v42, 0xa0, v162
	v_cvt_pk_bf16_f32 v36, v50, v52
	v_cvt_pk_bf16_f32 v37, v45, v47
	v_cvt_pk_bf16_f32 v38, v43, v54
	v_cvt_pk_bf16_f32 v39, v55, v39
	global_store_dwordx4 v[40:41], v[32:35], off
	global_store_dwordx4 v[40:41], v[36:39], off offset:64
	v_add_u32_e32 v40, 0xb0, v162
	v_lshlrev_b32_e32 v32, 8, v42
	v_and_b32_e32 v150, 0xfef00, v32
	v_lshl_add_u64 v[32:33], v[152:153], 0, v[150:151]
	global_load_dwordx4 v[44:47], v[32:33], off offset:16
	global_load_dwordx4 v[48:51], v[32:33], off
	global_load_dwordx4 v[52:55], v[32:33], off offset:32
	global_load_dwordx4 v[56:59], v[32:33], off offset:48
	v_mov_b32_e32 v36, v29
	v_mov_b32_e32 v37, v21
	v_mov_b32_e32 v34, v28
	v_mov_b32_e32 v35, v20
	v_pk_mul_f32 v[36:37], v[36:37], v[36:37]
	v_mov_b32_e32 v38, v31
	v_mov_b32_e32 v39, v23
	v_pk_fma_f32 v[34:35], v[34:35], v[34:35], v[36:37]
	v_mov_b32_e32 v36, v30
	v_mov_b32_e32 v37, v22
	v_pk_mul_f32 v[38:39], v[38:39], v[38:39]
	ds_read_b32 v41, v189 offset:640
	v_pk_fma_f32 v[36:37], v[36:37], v[36:37], v[38:39]
	v_mov_b32_e32 v38, v25
	v_mov_b32_e32 v39, v17
	v_pk_add_f32 v[34:35], v[34:35], v[36:37]
	v_mov_b32_e32 v36, v24
	v_mov_b32_e32 v37, v16
	v_pk_mul_f32 v[38:39], v[38:39], v[38:39]
	s_nop 0
	v_pk_fma_f32 v[36:37], v[36:37], v[36:37], v[38:39]
	v_mov_b32_e32 v38, v27
	v_mov_b32_e32 v39, v19
	v_pk_add_f32 v[34:35], v[34:35], v[36:37]
	v_mov_b32_e32 v36, v26
	v_mov_b32_e32 v37, v18
	v_pk_mul_f32 v[38:39], v[38:39], v[38:39]
	s_nop 0
	v_pk_fma_f32 v[36:37], v[36:37], v[36:37], v[38:39]
	s_nop 0
	v_pk_add_f32 v[34:35], v[36:37], v[34:35]
	s_nop 0
	v_add_f32_e32 v34, v34, v35
	v_mov_b32_e32 v35, v34
	s_nop 1
	v_permlane16_swap_b32_e32 v34, v35
	s_waitcnt lgkmcnt(0)
	v_add_f32_e32 v34, v34, v35
	v_mov_b32_e32 v35, v34
	s_nop 1
	v_permlane32_swap_b32_e32 v34, v35
	s_waitcnt lgkmcnt(0)
	v_add_f32_e32 v32, v34, v35
	v_mul_f32_e32 v32, v41, v32
	v_mul_f32_e32 v32, v41, v32
	v_fmamk_f32 v32, v32, 0x3c800000, v183
	v_mul_f32_e32 v33, 0x4f800000, v32
	v_cmp_gt_f32_e32 vcc, s92, v32
	v_lshlrev_b32_e32 v34, 8, v40
	v_and_b32_e32 v150, 0xfff00, v34
	v_cndmask_b32_e32 v32, v32, v33, vcc
	v_sqrt_f32_e32 v33, v32
	v_lshl_add_u64 v[64:65], v[152:153], 0, v[150:151]
	v_add_u32_e32 v34, -1, v33
	v_fma_f32 v35, -v34, v33, v32
	v_cmp_ge_f32_e64 s[4:5], 0, v35
	v_add_u32_e32 v35, 1, v33
	s_nop 0
	v_cndmask_b32_e64 v34, v33, v34, s[4:5]
	v_fma_f32 v33, -v35, v33, v32
	v_cmp_lt_f32_e64 s[4:5], 0, v33
	s_nop 1
	v_cndmask_b32_e64 v33, v34, v35, s[4:5]
	v_mul_f32_e32 v34, 0x37800000, v33
	v_cndmask_b32_e32 v33, v33, v34, vcc
	v_cmp_class_f32_e32 vcc, v32, v184
	s_nop 1
	v_cndmask_b32_e32 v43, v33, v32, vcc
	v_div_scale_f32 v68, s[4:5], v43, v43, v41
	v_rcp_f32_e32 v69, v68
	global_load_dwordx4 v[32:35], v[64:65], off offset:48
	global_load_dwordx4 v[36:39], v[64:65], off offset:32
	global_load_dwordx4 v[60:63], v[64:65], off offset:16
	s_nop 0
	global_load_dwordx4 v[64:67], v[64:65], off
	v_fma_f32 v70, -v68, v69, 1.0
	v_fmac_f32_e32 v69, v70, v69
	v_div_scale_f32 v70, vcc, v41, v43, v41
	v_mul_f32_e32 v71, v70, v69
	v_fma_f32 v72, -v68, v71, v70
	v_fmac_f32_e32 v71, v72, v69
	v_fma_f32 v68, -v68, v71, v70
	v_div_fmas_f32 v68, v68, v69, v71
	v_div_fixup_f32 v68, v68, v43, v41
	v_mov_b32_e32 v70, v24
	v_mov_b32_e32 v71, v28
	v_mov_b32_e32 v28, v25
	v_pk_mul_f32 v[70:71], v[70:71], v[68:69] op_sel_hi:[1,0]
	v_pk_mul_f32 v[24:25], v[28:29], v[68:69] op_sel_hi:[1,0]
	v_pk_mul_f32 v[70:71], v[174:175], v[70:71]
	v_pk_mul_f32 v[24:25], v[172:173], v[24:25]
	s_waitcnt vmcnt(6)
	v_pk_mul_f32 v[72:73], v[48:49], v[70:71] op_sel:[0,1] op_sel_hi:[1,0]
	v_pk_mul_f32 v[48:49], v[48:49], v[70:71]
	v_pk_mul_f32 v[28:29], v[50:51], v[24:25] op_sel:[0,1] op_sel_hi:[1,0]
	v_pk_mul_f32 v[24:25], v[50:51], v[24:25]
	v_add_f32_e32 v43, v48, v49
	v_add_f32_e32 v49, v24, v25
	v_mov_b32_e32 v24, v26
	v_mov_b32_e32 v25, v30
	v_pk_mul_f32 v[24:25], v[24:25], v[68:69] op_sel_hi:[1,0]
	v_sub_f32_e32 v48, v28, v29
	v_pk_mul_f32 v[24:25], v[120:121], v[24:25]
	v_mov_b32_e32 v30, v27
	v_pk_mul_f32 v[28:29], v[44:45], v[24:25] op_sel:[0,1] op_sel_hi:[1,0]
	v_pk_mul_f32 v[24:25], v[44:45], v[24:25]
	v_sub_f32_e32 v28, v28, v29
	v_add_f32_e32 v29, v24, v25
	v_pk_mul_f32 v[24:25], v[30:31], v[68:69] op_sel_hi:[1,0]
	v_sub_f32_e32 v41, v72, v73
	v_pk_mul_f32 v[24:25], v[170:171], v[24:25]
	s_nop 0
	v_pk_mul_f32 v[26:27], v[46:47], v[24:25] op_sel:[0,1] op_sel_hi:[1,0]
	v_pk_mul_f32 v[24:25], v[46:47], v[24:25]
	v_sub_f32_e32 v30, v26, v27
	v_add_f32_e32 v31, v24, v25
	v_mov_b32_e32 v25, v20
	v_mov_b32_e32 v20, v17
	v_mov_b32_e32 v24, v16
	v_pk_mul_f32 v[16:17], v[20:21], v[68:69] op_sel_hi:[1,0]
	v_pk_mul_f32 v[24:25], v[24:25], v[68:69] op_sel_hi:[1,0]
	v_pk_mul_f32 v[16:17], v[168:169], v[16:17]
	v_pk_mul_f32 v[24:25], v[122:123], v[24:25]
	s_waitcnt vmcnt(5)
	v_pk_mul_f32 v[20:21], v[54:55], v[16:17] op_sel:[0,1] op_sel_hi:[1,0]
	v_pk_mul_f32 v[16:17], v[54:55], v[16:17]
	v_pk_mul_f32 v[26:27], v[52:53], v[24:25] op_sel:[0,1] op_sel_hi:[1,0]
	v_add_f32_e32 v44, v16, v17
	v_mov_b32_e32 v16, v18
	v_mov_b32_e32 v17, v22
	v_pk_mul_f32 v[16:17], v[16:17], v[68:69] op_sel_hi:[1,0]
	v_pk_mul_f32 v[24:25], v[52:53], v[24:25]
	v_pk_mul_f32 v[16:17], v[112:113], v[16:17]
	v_sub_f32_e32 v26, v26, v27
	v_add_f32_e32 v27, v24, v25
	v_sub_f32_e32 v24, v20, v21
	s_waitcnt vmcnt(4)
	v_pk_mul_f32 v[20:21], v[56:57], v[16:17] op_sel:[0,1] op_sel_hi:[1,0]
	v_pk_mul_f32 v[16:17], v[56:57], v[16:17]
	v_mov_b32_e32 v22, v19
	v_add_f32_e32 v45, v16, v17
	v_pk_mul_f32 v[16:17], v[22:23], v[68:69] op_sel_hi:[1,0]
	v_sub_f32_e32 v20, v20, v21
	v_pk_mul_f32 v[16:17], v[166:167], v[16:17]
	v_mov_b32_e32 v22, v13
	v_pk_mul_f32 v[18:19], v[58:59], v[16:17] op_sel:[0,1] op_sel_hi:[1,0]
	v_pk_mul_f32 v[16:17], v[58:59], v[16:17]
	v_sub_f32_e32 v19, v18, v19
	v_mov_b32_e32 v23, v5
	v_add_f32_e32 v46, v16, v17
	v_cvt_pk_bf16_f32 v16, v41, v48
	v_cvt_pk_bf16_f32 v17, v28, v30
	v_cvt_pk_bf16_f32 v18, v26, v24
	v_cvt_pk_bf16_f32 v19, v20, v19
	v_mov_b32_e32 v20, v12
	v_mov_b32_e32 v21, v4
	v_pk_mul_f32 v[22:23], v[22:23], v[22:23]
	v_mov_b32_e32 v24, v15
	v_mov_b32_e32 v25, v7
	v_pk_fma_f32 v[20:21], v[20:21], v[20:21], v[22:23]
	v_mov_b32_e32 v22, v14
	v_mov_b32_e32 v23, v6
	v_pk_mul_f32 v[24:25], v[24:25], v[24:25]
	v_ashrrev_i32_e32 v41, 31, v40
	v_pk_fma_f32 v[22:23], v[22:23], v[22:23], v[24:25]
	v_mov_b32_e32 v24, v9
	v_mov_b32_e32 v25, v1
	v_pk_add_f32 v[20:21], v[20:21], v[22:23]
	v_mov_b32_e32 v22, v8
	v_mov_b32_e32 v23, v0
	v_pk_mul_f32 v[24:25], v[24:25], v[24:25]
	s_nop 0
	v_pk_fma_f32 v[22:23], v[22:23], v[22:23], v[24:25]
	v_mov_b32_e32 v24, v11
	v_mov_b32_e32 v25, v3
	v_pk_add_f32 v[20:21], v[20:21], v[22:23]
	v_mov_b32_e32 v22, v10
	v_mov_b32_e32 v23, v2
	v_pk_mul_f32 v[24:25], v[24:25], v[24:25]
	s_nop 0
	v_pk_fma_f32 v[22:23], v[22:23], v[22:23], v[24:25]
	s_nop 0
	v_pk_add_f32 v[20:21], v[22:23], v[20:21]
	s_nop 0
	v_add_f32_e32 v24, v20, v21
	v_mov_b32_e32 v25, v24
	s_nop 1
	v_permlane16_swap_b32_e32 v24, v25
	v_cvt_pk_bf16_f32 v20, v43, v49
	v_cvt_pk_bf16_f32 v21, v29, v31
	v_cvt_pk_bf16_f32 v22, v27, v44
	v_cvt_pk_bf16_f32 v23, v45, v46
	s_waitcnt lgkmcnt(0)
	v_add_f32_e32 v24, v24, v25
	v_mov_b32_e32 v25, v24
	s_nop 1
	v_permlane32_swap_b32_e32 v24, v25
	ds_read_b32 v26, v189 offset:704
	v_ashrrev_i32_e32 v43, 31, v42
	s_waitcnt lgkmcnt(1)
	v_add_f32_e32 v24, v24, v25
	s_waitcnt lgkmcnt(0)
	v_mul_f32_e32 v24, v26, v24
	v_mul_f32_e32 v24, v26, v24
	v_fmamk_f32 v24, v24, 0x3c800000, v183
	v_mul_f32_e32 v25, 0x4f800000, v24
	v_cmp_gt_f32_e32 vcc, s92, v24
	s_nop 1
	v_cndmask_b32_e32 v27, v24, v25, vcc
	v_sqrt_f32_e32 v28, v27
	v_lshlrev_b64 v[24:25], 11, v[42:43]
	v_lshl_add_u64 v[24:25], v[164:165], 0, v[24:25]
	global_store_dwordx4 v[24:25], v[16:19], off
	global_store_dwordx4 v[24:25], v[20:23], off offset:64
	v_add_u32_e32 v29, -1, v28
	v_fma_f32 v30, -v29, v28, v27
	v_cmp_ge_f32_e64 s[4:5], 0, v30
	v_add_u32_e32 v30, 1, v28
	v_mov_b32_e32 v19, v12
	v_cndmask_b32_e64 v29, v28, v29, s[4:5]
	v_fma_f32 v28, -v30, v28, v27
	v_cmp_lt_f32_e64 s[4:5], 0, v28
	v_mov_b32_e32 v12, v9
	s_nop 0
	v_cndmask_b32_e64 v28, v29, v30, s[4:5]
	v_mul_f32_e32 v29, 0x37800000, v28
	v_cndmask_b32_e32 v28, v28, v29, vcc
	v_cmp_class_f32_e32 vcc, v27, v184
	s_nop 1
	v_cndmask_b32_e32 v27, v28, v27, vcc
	v_div_scale_f32 v28, s[4:5], v27, v27, v26
	v_rcp_f32_e32 v29, v28
	s_nop 0
	v_fma_f32 v16, -v28, v29, 1.0
	v_fmac_f32_e32 v29, v16, v29
	v_div_scale_f32 v16, vcc, v26, v27, v26
	v_mul_f32_e32 v17, v16, v29
	v_fma_f32 v18, -v28, v17, v16
	v_fmac_f32_e32 v17, v18, v29
	v_fma_f32 v16, -v28, v17, v16
	v_div_fmas_f32 v16, v16, v29, v17
	v_div_fixup_f32 v16, v16, v27, v26
	v_mov_b32_e32 v18, v8
	v_pk_mul_f32 v[18:19], v[18:19], v[16:17] op_sel_hi:[1,0]
	s_nop 0
	v_pk_mul_f32 v[18:19], v[174:175], v[18:19]
	s_waitcnt vmcnt(2)
	v_pk_mul_f32 v[20:21], v[64:65], v[18:19] op_sel:[0,1] op_sel_hi:[1,0]
	v_pk_mul_f32 v[18:19], v[64:65], v[18:19]
	v_sub_f32_e32 v17, v20, v21
	v_pk_mul_f32 v[8:9], v[12:13], v[16:17] op_sel_hi:[1,0]
	v_add_f32_e32 v18, v18, v19
	v_pk_mul_f32 v[8:9], v[172:173], v[8:9]
	s_nop 0
	v_pk_mul_f32 v[12:13], v[66:67], v[8:9] op_sel:[0,1] op_sel_hi:[1,0]
	v_pk_mul_f32 v[8:9], v[66:67], v[8:9]
	v_sub_f32_e32 v19, v12, v13
	v_add_f32_e32 v20, v8, v9
	v_mov_b32_e32 v8, v10
	v_mov_b32_e32 v9, v14
	v_pk_mul_f32 v[8:9], v[8:9], v[16:17] op_sel_hi:[1,0]
	v_mov_b32_e32 v14, v11
	v_pk_mul_f32 v[8:9], v[120:121], v[8:9]
	s_nop 0
	v_pk_mul_f32 v[12:13], v[60:61], v[8:9] op_sel:[0,1] op_sel_hi:[1,0]
	v_pk_mul_f32 v[8:9], v[60:61], v[8:9]
	v_sub_f32_e32 v12, v12, v13
	v_add_f32_e32 v13, v8, v9
	v_pk_mul_f32 v[8:9], v[14:15], v[16:17] op_sel_hi:[1,0]
	s_nop 0
	v_pk_mul_f32 v[8:9], v[170:171], v[8:9]
	s_nop 0
	v_pk_mul_f32 v[10:11], v[62:63], v[8:9] op_sel:[0,1] op_sel_hi:[1,0]
	v_pk_mul_f32 v[8:9], v[62:63], v[8:9]
	v_sub_f32_e32 v14, v10, v11
	v_add_f32_e32 v15, v8, v9
	v_mov_b32_e32 v9, v4
	v_mov_b32_e32 v4, v1
	v_mov_b32_e32 v8, v0
	v_pk_mul_f32 v[0:1], v[4:5], v[16:17] op_sel_hi:[1,0]
	v_pk_mul_f32 v[8:9], v[8:9], v[16:17] op_sel_hi:[1,0]
	v_pk_mul_f32 v[0:1], v[168:169], v[0:1]
	v_pk_mul_f32 v[8:9], v[122:123], v[8:9]
	v_pk_mul_f32 v[4:5], v[38:39], v[0:1] op_sel:[0,1] op_sel_hi:[1,0]
	v_pk_mul_f32 v[0:1], v[38:39], v[0:1]
	v_sub_f32_e32 v21, v4, v5
	v_add_f32_e32 v22, v0, v1
	v_mov_b32_e32 v0, v2
	v_mov_b32_e32 v1, v6
	v_pk_mul_f32 v[0:1], v[0:1], v[16:17] op_sel_hi:[1,0]
	v_mov_b32_e32 v6, v3
	v_pk_mul_f32 v[0:1], v[112:113], v[0:1]
	v_pk_mul_f32 v[10:11], v[36:37], v[8:9] op_sel:[0,1] op_sel_hi:[1,0]
	v_pk_mul_f32 v[4:5], v[32:33], v[0:1] op_sel:[0,1] op_sel_hi:[1,0]
	v_pk_mul_f32 v[0:1], v[32:33], v[0:1]
	v_pk_mul_f32 v[8:9], v[36:37], v[8:9]
	v_add_f32_e32 v23, v0, v1
	v_pk_mul_f32 v[0:1], v[6:7], v[16:17] op_sel_hi:[1,0]
	v_sub_f32_e32 v10, v10, v11
	v_pk_mul_f32 v[0:1], v[166:167], v[0:1]
	v_add_f32_e32 v11, v8, v9
	v_pk_mul_f32 v[2:3], v[34:35], v[0:1] op_sel:[0,1] op_sel_hi:[1,0]
	v_pk_mul_f32 v[0:1], v[34:35], v[0:1]
	v_sub_f32_e32 v3, v2, v3
	v_add_f32_e32 v7, v0, v1
	v_lshlrev_b64 v[0:1], 11, v[40:41]
	v_sub_f32_e32 v4, v4, v5
	v_lshl_add_u64 v[8:9], v[164:165], 0, v[0:1]
	v_cvt_pk_bf16_f32 v0, v17, v19
	v_cvt_pk_bf16_f32 v1, v12, v14
	v_cvt_pk_bf16_f32 v2, v10, v21
	v_cvt_pk_bf16_f32 v3, v4, v3
	v_cvt_pk_bf16_f32 v4, v18, v20
	v_cvt_pk_bf16_f32 v5, v13, v15
	v_cvt_pk_bf16_f32 v6, v11, v22
	v_cvt_pk_bf16_f32 v7, v23, v7
	global_store_dwordx4 v[8:9], v[0:3], off
	global_store_dwordx4 v[8:9], v[4:7], off offset:64
	s_andn2_b64 vcc, exec, s[0:1]
	s_mov_b64 s[0:1], -1
	s_cbranch_vccnz .LBB0_316
	s_branch .LBB0_336
